# s5 carry scan: complex recurrence as two packed fma per step (same operations), LDS waits every second step
# baseline (speedup 1.0000x reference)
.Ls5_nopf:
	s_and_saveexec_b64 s[8:9], s[2:3]
	s_cbranch_execz .LBB0_722
	v_or_b32_e32 v32, s88, v147
	v_lshl_add_u64 v[34:35], v[32:33], 2, s[0:1]
	global_load_dwordx2 v[34:35], v[34:35], off
	s_and_b64 s[30:31], s[10:11], exec
	s_cselect_b32 s24, 0, 0x105f0
	s_movk_i32 s25, 0x210
	s_cselect_b32 s25, s25, 0xfffffdf0
	v_add_u32_e32 v40, s24, v155
	v_add_u32_e32 v41, s25, v40
	v_add_u32_e32 v42, s25, v41
	v_add_u32_e32 v43, s25, v42
	v_add_u32_e32 v44, s25, v43
	v_add_u32_e32 v45, s25, v44
	v_add_u32_e32 v46, s25, v45
	v_add_u32_e32 v47, s25, v46
	s_lshl_b32 s24, s25, 3
	ds_read2st64_b32 v[80:81], v40 offset1:1
	ds_read2st64_b32 v[82:83], v41 offset1:1
	ds_read2st64_b32 v[84:85], v42 offset1:1
	ds_read2st64_b32 v[86:87], v43 offset1:1
	ds_read2st64_b32 v[88:89], v44 offset1:1
	ds_read2st64_b32 v[90:91], v45 offset1:1
	ds_read2st64_b32 v[92:93], v46 offset1:1
	ds_read2st64_b32 v[94:95], v47 offset1:1
	v_mov_b32_e32 v38, 0
	v_mov_b32_e32 v39, 0
	s_mov_b32 s7, 16
	s_waitcnt vmcnt(0) lgkmcnt(0)
	v_xor_b32_e32 v96, 0x80000000, v35
	v_mov_b32_e32 v97, v35
	v_mov_b32_e32 v98, v34
	v_mov_b32_e32 v99, v34
.Ls5_scan:
	s_waitcnt lgkmcnt(12)
	ds_write2st64_b32 v40, v38, v39 offset1:1
	v_pk_fma_f32 v[36:37], v[96:97], v[38:39], v[80:81] op_sel:[0,1,0] op_sel_hi:[1,0,1]
	v_pk_fma_f32 v[38:39], v[98:99], v[38:39], v[36:37]
	v_add_u32_e32 v40, s24, v40
	ds_read2st64_b32 v[80:81], v40 offset1:1
	ds_write2st64_b32 v41, v38, v39 offset1:1
	v_pk_fma_f32 v[36:37], v[96:97], v[38:39], v[82:83] op_sel:[0,1,0] op_sel_hi:[1,0,1]
	v_pk_fma_f32 v[38:39], v[98:99], v[38:39], v[36:37]
	v_add_u32_e32 v41, s24, v41
	ds_read2st64_b32 v[82:83], v41 offset1:1
	s_waitcnt lgkmcnt(12)
	ds_write2st64_b32 v42, v38, v39 offset1:1
	v_pk_fma_f32 v[36:37], v[96:97], v[38:39], v[84:85] op_sel:[0,1,0] op_sel_hi:[1,0,1]
	v_pk_fma_f32 v[38:39], v[98:99], v[38:39], v[36:37]
	v_add_u32_e32 v42, s24, v42
	ds_read2st64_b32 v[84:85], v42 offset1:1
	ds_write2st64_b32 v43, v38, v39 offset1:1
	v_pk_fma_f32 v[36:37], v[96:97], v[38:39], v[86:87] op_sel:[0,1,0] op_sel_hi:[1,0,1]
	v_pk_fma_f32 v[38:39], v[98:99], v[38:39], v[36:37]
	v_add_u32_e32 v43, s24, v43
	ds_read2st64_b32 v[86:87], v43 offset1:1
	s_waitcnt lgkmcnt(12)
	ds_write2st64_b32 v44, v38, v39 offset1:1
	v_pk_fma_f32 v[36:37], v[96:97], v[38:39], v[88:89] op_sel:[0,1,0] op_sel_hi:[1,0,1]
	v_pk_fma_f32 v[38:39], v[98:99], v[38:39], v[36:37]
	v_add_u32_e32 v44, s24, v44
	ds_read2st64_b32 v[88:89], v44 offset1:1
	ds_write2st64_b32 v45, v38, v39 offset1:1
	v_pk_fma_f32 v[36:37], v[96:97], v[38:39], v[90:91] op_sel:[0,1,0] op_sel_hi:[1,0,1]
	v_pk_fma_f32 v[38:39], v[98:99], v[38:39], v[36:37]
	v_add_u32_e32 v45, s24, v45
	ds_read2st64_b32 v[90:91], v45 offset1:1
	s_waitcnt lgkmcnt(12)
	ds_write2st64_b32 v46, v38, v39 offset1:1
	v_pk_fma_f32 v[36:37], v[96:97], v[38:39], v[92:93] op_sel:[0,1,0] op_sel_hi:[1,0,1]
	v_pk_fma_f32 v[38:39], v[98:99], v[38:39], v[36:37]
	v_add_u32_e32 v46, s24, v46
	ds_read2st64_b32 v[92:93], v46 offset1:1
	ds_write2st64_b32 v47, v38, v39 offset1:1
	v_pk_fma_f32 v[36:37], v[96:97], v[38:39], v[94:95] op_sel:[0,1,0] op_sel_hi:[1,0,1]
	v_pk_fma_f32 v[38:39], v[98:99], v[38:39], v[36:37]
	v_add_u32_e32 v47, s24, v47
	ds_read2st64_b32 v[94:95], v47 offset1:1
	s_add_i32 s7, s7, -1
	s_cmp_lg_u32 s7, 0
	s_cbranch_scc1 .Ls5_scan
